# attention unit queue: next unit index claimed one unit ahead (atomic latency hidden behind the unit body)
# baseline (speedup 1.0000x reference)
; __global__ void __launch_bounds__(512) mega(Params P) {
;     ...
;     {
;       const float* ptot = (const float*)(ws + WS_PTOT);
;       float* offt = (float*)(smem + AT_OFF);
;       const int seq = tid >> 5, l5 = tid & 31, bb = seq >> 3, hh_ = seq & 7;
;       float v0 = ptot[(bb * 128 + 4 * l5 + 0) * 8 + hh_], v1 = ptot[(bb * 128 + 4 * l5 + 1) * 8 + hh_], v2 = ptot[(bb * 128 + 4 * l5 + 2) * 8 + hh_], v3 = ptot[(bb * 128 + 4 * l5 + 3) * 8 + hh_];
;       const float tot = (v0 + v1) + (v2 + v3);
;       float inc = tot;
; #pragma unroll
;       for (int o_ = 1; o_ < 32; o_ <<= 1) { const float nb_ = __shfl_up(inc, o_, 32); if (l5 >= o_) inc += nb_; }
;       const float ex = inc - tot;
;       offt[seq * 128 + 4 * l5 + 0] = ex; offt[seq * 128 + 4 * l5 + 1] = ex + v0; offt[seq * 128 + 4 * l5 + 2] = ex + v0 + v1; offt[seq * 128 + 4 * l5 + 3] = ex + v0 + v1 + v2;
;     }
.LBB0_152:
	s_or_b64 exec, exec, s[2:3]
	v_lshlrev_b32_e32 v2, 2, v176
	v_and_b32_e32 v1, 31, v176
	v_and_b32_e32 v2, 0xc00, v2
	v_lshrrev_b32_e32 v0, 5, v176
	v_lshl_or_b32 v2, v1, 5, v2
	v_and_or_b32 v3, v0, 7, v2
	v_lshlrev_b32_e32 v3, 2, v3
	v_or_b32_e32 v2, v0, v2
	v_mov_b32_e32 v4, 0x60
	v_lshl_or_b32 v2, v2, 2, v4
	global_load_dword v4, v3, s[0:1]
	global_load_dword v5, v3, s[0:1] offset:32
	global_load_dword v6, v3, s[0:1] offset:64
	global_load_dword v7, v2, s[0:1]
	v_mbcnt_hi_u32_b32 v156, -1, v179
	v_and_b32_e32 v2, 0x60, v156
	v_add_u32_e32 v3, -1, v156
	v_cmp_lt_i32_e32 vcc, v3, v2
	v_add_u32_e32 v8, -2, v156
	v_add_u32_e32 v9, -4, v156
	v_cndmask_b32_e32 v3, v3, v156, vcc
	v_lshlrev_b32_e32 v3, 2, v3
	v_cmp_lt_i32_e32 vcc, v8, v2
	v_add_u32_e32 v10, -8, v156
	v_add_u32_e32 v11, -16, v156
	v_cndmask_b32_e32 v8, v8, v156, vcc
	v_cmp_lt_i32_e32 vcc, v9, v2
	s_add_u32 s0, s82, 0x110000
	s_addc_u32 s1, s83, 0
	v_cndmask_b32_e32 v9, v9, v156, vcc
	v_cmp_lt_i32_e32 vcc, v10, v2
	v_lshlrev_b32_e32 v0, 9, v0
	s_add_i32 s2, 0, 0x23d00
	v_cndmask_b32_e32 v10, v10, v156, vcc
	v_cmp_lt_i32_e32 vcc, v11, v2
	v_lshlrev_b32_e32 v12, 4, v1
	v_and_b32_e32 v154, 64, v156
	v_cndmask_b32_e32 v2, v11, v156, vcc
	v_cmp_eq_u32_e32 vcc, 0, v1
	v_add3_u32 v11, s2, v0, v12
	v_lshlrev_b32_e32 v0, 2, v8
	v_lshlrev_b32_e32 v8, 2, v9
	v_xor_b32_e32 v13, 32, v156
	v_add_u32_e32 v157, 64, v154
	v_lshlrev_b32_e32 v9, 2, v10
	v_lshlrev_b32_e32 v2, 2, v2
	s_add_u32 s62, s82, 0x10c00000
	s_addc_u32 s63, s83, 0
	s_add_u32 s18, s82, 0x1cc00000
	s_addc_u32 s19, s83, 0
	s_add_i32 s36, 0, 0x23c60
	s_mov_b32 s3, 0
	v_mov_b32_e32 v113, 0
	s_movk_i32 s5, 0x7ff
	s_movk_i32 s28, 0x80
	s_movk_i32 s29, 0x1800
	s_mov_b32 s4, 0x3fb8aa3b
	s_mov_b32 s30, 0xc2a00000
	s_mov_b64 s[14:15], 0x1000
	s_movk_i32 s31, 0x90
	s_movk_i32 s33, 0x110
	s_movk_i32 s34, 0x100
	s_mov_b64 s[16:17], 0xcc00400
	s_mov_b32 s35, 0xcc00000
	s_add_i32 s37, 0, 0x23800
	s_add_i32 s38, 0, 0x23c00
	s_add_i32 s39, 0, 0x23c10
	v_mov_b32_e32 v127, s36
	v_mov_b32_e32 v128, 0xff800000
	s_waitcnt vmcnt(2)
	v_add_f32_e32 v14, v4, v5
	s_waitcnt vmcnt(0)
	v_add_f32_e32 v7, v6, v7
	v_add_f32_e32 v7, v14, v7
	ds_bpermute_b32 v3, v3, v7
	s_waitcnt lgkmcnt(0)
	v_add_f32_e32 v3, v7, v3
	v_cndmask_b32_e32 v3, v3, v7, vcc
	ds_bpermute_b32 v0, v0, v3
	v_cmp_gt_u32_e32 vcc, 2, v1
	s_waitcnt lgkmcnt(0)
	v_add_f32_e32 v0, v3, v0
	v_cndmask_b32_e32 v0, v0, v3, vcc
	ds_bpermute_b32 v3, v8, v0
	v_cmp_lt_i32_e32 vcc, v13, v157
	s_waitcnt lgkmcnt(0)
	v_add_f32_e32 v3, v0, v3
	v_cndmask_b32_e32 v8, v156, v13, vcc
	v_cmp_gt_u32_e32 vcc, 4, v1
	v_lshlrev_b32_e32 v155, 2, v8
	s_nop 0
	v_cndmask_b32_e32 v0, v3, v0, vcc
	ds_bpermute_b32 v3, v9, v0
	v_cmp_gt_u32_e32 vcc, 8, v1
	s_waitcnt lgkmcnt(0)
	v_add_f32_e32 v3, v0, v3
	v_cndmask_b32_e32 v0, v3, v0, vcc
	ds_bpermute_b32 v2, v2, v0
	v_cmp_gt_u32_e32 vcc, 16, v1
	s_waitcnt lgkmcnt(0)
	v_add_f32_e32 v2, v0, v2
	v_cndmask_b32_e32 v0, v2, v0, vcc
	v_sub_f32_e32 v0, v0, v7
	v_add_f32_e32 v1, v4, v0
	v_add_f32_e32 v2, v5, v1
	v_add_f32_e32 v3, v6, v2
	ds_write_b128 v11, v[0:3]
	s_mov_b32 s98, 0
	s_branch .LBB0_155

; __global__ void __launch_bounds__(512) mega(Params P) {
;     ...
;     for (;;) {
;       __syncthreads();
;       if (tid == 0) hs[8] = (int)atomicAdd(ctr, 1u);
;       __syncthreads();
;       const int u = hs[8];
;       if (u >= 2048) break;
.LBB0_155:
	s_waitcnt lgkmcnt(0)
	s_barrier
	s_and_saveexec_b64 s[6:7], s[94:95]
	s_cbranch_execz .LBB0_159
	s_mov_b64 s[10:11], exec
	v_mbcnt_lo_u32_b32 v0, s10, 0
	v_mbcnt_hi_u32_b32 v0, s11, v0
	v_cmp_eq_u32_e32 vcc, 0, v0
	s_and_saveexec_b64 s[8:9], vcc
	s_cbranch_execz .LBB0_158
	s_bcnt1_i32_b64 s2, s[10:11]
	s_cmp_eq_u32 s98, 0
	s_cbranch_scc0 .Luq_have
	v_mov_b32_e32 v236, s2
	global_atomic_add v236, v113, v236, s[0:1] sc0
	s_mov_b32 s98, 1
.Luq_have:
	s_waitcnt vmcnt(0)
	v_mov_b32_e32 v1, v236
	v_mov_b32_e32 v236, s2
	global_atomic_add v236, v113, v236, s[0:1] sc0
.LBB0_158:
	s_or_b64 exec, exec, s[8:9]
	v_readfirstlane_b32 s2, v1
	v_mov_b32_e32 v1, s36
	s_nop 0
	v_add_u32_e32 v0, s2, v0
	ds_write_b32 v1, v0
